# attention steady loop: the three LDS-DMA issues of each step moved from after the QK block to the step head
# baseline (speedup 1.0000x reference)
.LBB0_90:
	s_lshl_b32 s21, s28, 1
	v_add_u32_e32 v213, s21, v225
	v_lshl_add_u64 v[218:219], v[230:231], 0, s[36:37]
	v_lshl_add_u64 v[124:125], v[218:219], 0, s[92:93]
	s_add_i32 s21, s27, s18
	v_lshl_add_u64 v[216:217], v[214:215], 0, s[36:37]
	s_mov_b32 s24, m0
	s_mov_b32 m0, s21
	s_nop 0
	global_load_lds_dwordx4 v[124:125], off
	s_mov_b32 m0, s24
	v_lshl_add_u64 v[124:125], v[216:217], 0, s[0:1]
	s_lshl_b32 s21, s25, 1
	s_add_i32 s21, s21, s19
	s_mov_b32 s24, m0
	s_mov_b32 m0, s21
	s_nop 0
	global_load_lds_dwordx4 v[124:125], off
	s_mov_b32 m0, s24
	v_lshl_add_u64 v[124:125], v[216:217], 0, s[68:69]
	s_addk_i32 s21, 0x2000
	s_mov_b32 s24, m0
	s_mov_b32 m0, s21
	s_nop 0
	global_load_lds_dwordx4 v[124:125], off
	s_mov_b32 m0, s24
	ds_read_b64_tr_b16 v[208:209], v213 offset:24576
	ds_read_b64_tr_b16 v[210:211], v213 offset:25088
	s_waitcnt lgkmcnt(9)
	v_mfma_f32_32x32x16_bf16 v[128:143], v[204:207], v[172:175], v[64:79]
	v_add_f32_e32 v112, v96, v97
	v_add_f32_e32 v112, v98, v112
	v_add_f32_e32 v112, v99, v112
	v_add_f32_e32 v112, v100, v112
	v_add_f32_e32 v112, v101, v112
	v_cvt_pk_bf16_f32 v164, v96, v97
	v_cvt_pk_bf16_f32 v165, v98, v99
	ds_read_b64_tr_b16 v[204:205], v213 offset:28672
	ds_read_b64_tr_b16 v[206:207], v213 offset:29184
	v_add_f32_e32 v96, v102, v112
	s_waitcnt lgkmcnt(10)
	v_mfma_f32_32x32x16_bf16 v[128:143], v[196:199], v[168:171], v[128:143]
	v_add_f32_e32 v96, v103, v96
	v_add_f32_e32 v96, v104, v96
	v_add_f32_e32 v144, v105, v96
	v_cvt_pk_bf16_f32 v166, v100, v101
	v_cvt_pk_bf16_f32 v167, v102, v103
	ds_read_b64_tr_b16 v[96:97], v213 offset:25600
	ds_read_b64_tr_b16 v[98:99], v213 offset:26112
	s_waitcnt lgkmcnt(11)
	v_mfma_f32_32x32x16_bf16 v[128:143], v[188:191], v[160:163], v[128:143]
	v_add_f32_e32 v100, v106, v144
	v_add_f32_e32 v100, v107, v100
	v_add_f32_e32 v100, v108, v100
	v_add_f32_e32 v144, v109, v100
	v_cvt_pk_bf16_f32 v156, v104, v105
	v_cvt_pk_bf16_f32 v157, v106, v107
	ds_read_b64_tr_b16 v[100:101], v213 offset:29696
	ds_read_b64_tr_b16 v[102:103], v213 offset:30208
	s_waitcnt lgkmcnt(12)
	v_mfma_f32_32x32x16_bf16 v[128:143], v[180:183], v[152:155], v[128:143]
	v_add_f32_e32 v104, v110, v144
	v_add_f32_e32 v104, v111, v104
	v_add_f32_e32 v104, v80, v104
	v_add_f32_e32 v144, v81, v104
	v_cvt_pk_bf16_f32 v158, v108, v109
	v_cvt_pk_bf16_f32 v159, v110, v111
	ds_read_b64_tr_b16 v[104:105], v213 offset:26624
	ds_read_b64_tr_b16 v[106:107], v213 offset:27136
	s_waitcnt lgkmcnt(13)
	v_mfma_f32_32x32x16_bf16 v[112:127], v[200:203], v[172:175], v[64:79]
	v_add_f32_e32 v108, v82, v144
	v_add_f32_e32 v108, v83, v108
	v_add_f32_e32 v108, v84, v108
	v_add_f32_e32 v144, v85, v108
	v_cvt_pk_bf16_f32 v148, v80, v81
	v_cvt_pk_bf16_f32 v149, v82, v83
	ds_read_b64_tr_b16 v[108:109], v213 offset:30720
	ds_read_b64_tr_b16 v[110:111], v213 offset:31232
	s_waitcnt lgkmcnt(14)
	v_mfma_f32_32x32x16_bf16 v[112:127], v[192:195], v[168:171], v[112:127]
	v_add_f32_e32 v80, v86, v144
	v_add_f32_e32 v80, v87, v80
	v_add_f32_e32 v80, v88, v80
	v_add_f32_e32 v80, v89, v80
	v_cvt_pk_bf16_f32 v150, v84, v85
	v_cvt_pk_bf16_f32 v151, v86, v87
	ds_read_b64_tr_b16 v[84:85], v213 offset:27648
	ds_read_b64_tr_b16 v[86:87], v213 offset:28160
	s_waitcnt lgkmcnt(14)
	v_mfma_f32_32x32x16_bf16 v[112:127], v[184:187], v[160:163], v[112:127]
	v_add_f32_e32 v80, v90, v80
	v_add_f32_e32 v80, v91, v80
	v_add_f32_e32 v80, v92, v80
	v_add_f32_e32 v80, v93, v80
	v_cvt_pk_bf16_f32 v144, v88, v89
	v_cvt_pk_bf16_f32 v145, v90, v91
	ds_read_b64_tr_b16 v[88:89], v213 offset:31744
	ds_read_b64_tr_b16 v[90:91], v213 offset:32256
	v_mfma_f32_32x32x16_bf16 v[112:127], v[176:179], v[152:155], v[112:127]
	v_add_f32_e32 v80, v94, v80
	v_add_f32_e32 v80, v95, v80
	v_add_f32_e32 v82, 0, v80
	v_cvt_pk_bf16_f32 v146, v92, v93
	v_cvt_pk_bf16_f32 v147, v94, v95
	s_nop 5
	v_max_f32_e32 v80, v129, v129
	v_max_f32_e32 v81, v128, v128
	v_max_f32_e32 v80, v81, v80
	v_max3_f32 v81, v130, v131, v113
	v_max3_f32 v80, v80, v112, v114
	v_max3_f32 v80, v80, v115, v132
	v_max3_f32 v81, v81, v134, v135
	v_max3_f32 v80, v80, v133, v116
	v_max3_f32 v81, v81, v118, v119
	v_max3_f32 v80, v80, v117, v136
	v_max3_f32 v81, v81, v138, v139
	v_max3_f32 v80, v80, v137, v120
	v_max3_f32 v81, v81, v122, v123
	v_max3_f32 v80, v80, v121, v140
	v_max3_f32 v81, v81, v142, v143
	v_max3_f32 v80, v80, v141, v124
	v_max3_f32 v81, v81, v126, v127
	v_max3_f32 v80, v80, v125, v81
	v_mov_b32_e32 v81, v80
	s_nop 1
	v_permlane32_swap_b32_e32 v80, v81
	v_max_f32_e32 v81, v81, v81
	v_max_f32_e32 v80, v80, v80
	v_max_f32_e32 v80, v80, v81
	v_cmp_lt_f32_e32 vcc, s74, v80
	s_cmp_lg_u64 vcc, 0
	v_add_f32_e32 v227, v227, v82
	s_cselect_b64 s[38:39], -1, 0
	s_cbranch_vccnz .LBB0_98

.LBB0_93:
	s_add_i32 s21, s25, 0x2000
	s_cmpk_lg_i32 s25, 0x4000
	s_cselect_b32 s21, s21, 0
	s_lshl_b32 s24, s27, 1
	v_add_u32_e32 v228, s24, v225
	s_mov_b64 s[28:29], 0x460000
	v_lshl_add_u64 v[84:85], v[218:219], 0, s[28:29]
	s_add_i32 s24, s25, s18
	s_mov_b64 s[28:29], 0x12aa1000
	s_mov_b32 s27, m0
	s_mov_b32 m0, s24
	s_nop 0
	global_load_lds_dwordx4 v[84:85], off
	s_mov_b32 m0, s27
	v_lshl_add_u64 v[84:85], v[216:217], 0, s[28:29]
	s_lshl_b32 s24, s21, 1
	s_mov_b64 s[28:29], 0x12aa1080
	s_add_i32 s24, s24, s19
	s_mov_b32 s27, m0
	s_mov_b32 m0, s24
	s_nop 0
	global_load_lds_dwordx4 v[84:85], off
	s_mov_b32 m0, s27
	v_lshl_add_u64 v[84:85], v[216:217], 0, s[28:29]
	s_addk_i32 s24, 0x2000
	s_mov_b32 s27, m0
	s_mov_b32 m0, s24
	s_nop 0
	global_load_lds_dwordx4 v[84:85], off
	s_mov_b32 m0, s27
	ds_read_b64_tr_b16 v[204:205], v228 offset:24576
	ds_read_b64_tr_b16 v[206:207], v228 offset:25088
	v_mfma_f32_32x32x16_bf16 v[96:111], v[80:83], v[172:175], v[64:79]
	v_add_f32_e32 v84, v128, v129
	v_add_f32_e32 v84, v130, v84
	v_add_f32_e32 v84, v131, v84
	v_add_f32_e32 v84, v132, v84
	v_add_f32_e32 v84, v133, v84
	v_cvt_pk_bf16_f32 v164, v128, v129
	v_cvt_pk_bf16_f32 v165, v130, v131
	ds_read_b64_tr_b16 v[208:209], v228 offset:28672
	ds_read_b64_tr_b16 v[210:211], v228 offset:29184
	v_add_f32_e32 v80, v134, v84
	v_add_f32_e32 v80, v135, v80
	v_add_f32_e32 v80, v136, v80
	v_add_f32_e32 v144, v137, v80
	v_mfma_f32_32x32x16_bf16 v[96:111], v[200:203], v[168:171], v[96:111]
	v_cvt_pk_bf16_f32 v166, v132, v133
	v_cvt_pk_bf16_f32 v167, v134, v135
	ds_read_b64_tr_b16 v[128:129], v228 offset:25600
	ds_read_b64_tr_b16 v[130:131], v228 offset:26112
	v_mfma_f32_32x32x16_bf16 v[96:111], v[188:191], v[160:163], v[96:111]
	v_add_f32_e32 v132, v138, v144
	v_add_f32_e32 v132, v139, v132
	v_add_f32_e32 v132, v140, v132
	v_add_f32_e32 v144, v141, v132
	v_cvt_pk_bf16_f32 v156, v136, v137
	v_cvt_pk_bf16_f32 v157, v138, v139
	ds_read_b64_tr_b16 v[132:133], v228 offset:29696
	ds_read_b64_tr_b16 v[134:135], v228 offset:30208
	v_mfma_f32_32x32x16_bf16 v[96:111], v[180:183], v[152:155], v[96:111]
	v_add_f32_e32 v136, v142, v144
	v_add_f32_e32 v136, v143, v136
	v_add_f32_e32 v136, v112, v136
	v_add_f32_e32 v144, v113, v136
	v_cvt_pk_bf16_f32 v158, v140, v141
	v_cvt_pk_bf16_f32 v159, v142, v143
	ds_read_b64_tr_b16 v[136:137], v228 offset:26624
	ds_read_b64_tr_b16 v[138:139], v228 offset:27136
	v_mfma_f32_32x32x16_bf16 v[80:95], v[196:199], v[172:175], v[64:79]
	v_add_f32_e32 v140, v114, v144
	v_add_f32_e32 v140, v115, v140
	v_add_f32_e32 v140, v116, v140
	v_add_f32_e32 v140, v117, v140
	v_cvt_pk_bf16_f32 v148, v112, v113
	v_cvt_pk_bf16_f32 v149, v114, v115
	ds_read_b64_tr_b16 v[112:113], v228 offset:30720
	ds_read_b64_tr_b16 v[114:115], v228 offset:31232
	v_mfma_f32_32x32x16_bf16 v[80:95], v[192:195], v[168:171], v[80:95]
	v_add_f32_e32 v140, v118, v140
	v_add_f32_e32 v140, v119, v140
	v_add_f32_e32 v140, v120, v140
	v_add_f32_e32 v140, v121, v140
	v_cvt_pk_bf16_f32 v150, v116, v117
	v_cvt_pk_bf16_f32 v151, v118, v119
	ds_read_b64_tr_b16 v[116:117], v228 offset:27648
	ds_read_b64_tr_b16 v[118:119], v228 offset:28160
	v_mfma_f32_32x32x16_bf16 v[80:95], v[184:187], v[160:163], v[80:95]
	v_add_f32_e32 v140, v122, v140
	v_add_f32_e32 v140, v123, v140
	v_add_f32_e32 v140, v124, v140
	v_add_f32_e32 v140, v125, v140
	v_cvt_pk_bf16_f32 v144, v120, v121
	v_cvt_pk_bf16_f32 v145, v122, v123
	ds_read_b64_tr_b16 v[120:121], v228 offset:31744
	ds_read_b64_tr_b16 v[122:123], v228 offset:32256
	v_mfma_f32_32x32x16_bf16 v[80:95], v[176:179], v[152:155], v[80:95]
	v_add_f32_e32 v140, v126, v140
	v_add_f32_e32 v140, v127, v140
	v_add_f32_e32 v140, 0, v140
	v_cvt_pk_bf16_f32 v146, v124, v125
	v_cvt_pk_bf16_f32 v147, v126, v127
	s_nop 5
	v_max_f32_e32 v124, v97, v97
	v_max_f32_e32 v125, v96, v96
	v_max_f32_e32 v124, v125, v124
	v_max3_f32 v125, v98, v99, v81
	v_max3_f32 v124, v124, v80, v82
	v_max3_f32 v124, v124, v83, v100
	v_max3_f32 v125, v125, v102, v103
	v_max3_f32 v124, v124, v101, v84
	v_max3_f32 v125, v125, v86, v87
	v_max3_f32 v124, v124, v85, v104
	v_max3_f32 v125, v125, v106, v107
	v_max3_f32 v124, v124, v105, v88
	v_max3_f32 v125, v125, v90, v91
	v_max3_f32 v124, v124, v89, v108
	v_max3_f32 v125, v125, v110, v111
	v_max3_f32 v124, v124, v109, v92
	v_max3_f32 v125, v125, v94, v95
	v_max3_f32 v124, v124, v93, v125
	v_mov_b32_e32 v125, v124
	s_nop 1
	v_permlane32_swap_b32_e32 v124, v125
	v_max_f32_e32 v125, v125, v125
	v_max_f32_e32 v124, v124, v124
	v_max_f32_e32 v124, v124, v125
	v_cmp_lt_f32_e32 vcc, s74, v124
	s_cmp_lg_u64 vcc, 0
	v_add_f32_e32 v227, v227, v140
	s_cselect_b64 s[38:39], -1, 0
	s_cbranch_vccnz .LBB0_101
